# dil loop: next item's Q fragments prefetched one item ahead (into 4 unused quads beside the K/V prefetch); loop top loads Q only for the first item; later-loop placement preserved by padding
# speedup vs baseline: 1.0084x; 1.0084x over previous
; #define LAS __attribute__((address_space(3)))
; DI void dil_store(const DilPre& P, bf16x8 (&qf)[4], ldsp lds, const bf16_t* proj, const float* rope, int item, int tid, int wid, int lane) {
;     const DilItem d = dil_decode(item);
;     const ldsp Kb = lds, Vb = lds + 256 * DIL_KS;
;     const int li = lane & 15, quad = lane >> 4;
;     const int tq = (128 * d.jb + 16 * wid + li) * d.r + d.ph;
;     float4 qcs[4], kcs[4];
;     {
;         const bf16_t* qsrc = proj + (d.rowbase + tq) * DIL_N + d.qcol + quad * 8;
; #pragma unroll
;         for (int ks = 0; ks < 4; ++ks) qf[ks] = *(const bf16x8*)(qsrc + ks * 32);
;         const float4* rp = (const float4*)(rope + (size_t)tq * 32 + 16 * (quad & 1));
; #pragma unroll
;         for (int jj = 0; jj < 4; ++jj) qcs[jj] = rp[jj];
;     }
;     const int prow = tid >> 1, pc = tid & 1, psp = d.s_k0 + prow;
;     u32x4 kp1 = (u32x4){0u, 0u, 0u, 0u}, kp2 = kp1;
;     {
;         const int tok = (psp >= 0 ? psp : 0) * d.r + d.ph;
;         const bf16_t* ksrc = proj + (d.rowbase + tok) * DIL_N + d.qcol + 768 + 8 * pc;
;         kp1 = *(const u32x4*)ksrc; kp2 = *(const u32x4*)(ksrc + 16);
;         const float4* rp = (const float4*)(rope + (size_t)tok * 32 + 16 * pc);
; #pragma unroll
;         for (int jj = 0; jj < 4; ++jj) kcs[jj] = rp[jj];
;     }
; #pragma unroll
;     for (int i = 0; i < 6; ++i) {
;         const int e = tid + i * 512, row = e / 12, ch = 4 + (e - row * 12), sp = d.s_k0 + row;
;         if (sp >= 0) *(LAS u32x4*)(Kb + row * DIL_KS + ch * 16) = P.kc[i];
.LBB0_331:
	s_and_b32 s98, s15, 7
	s_lshl_b32 s98, s98, 5
	s_bfe_u32 s99, s15, 0x10007
	s_lshl_b32 s99, s99, 4
	s_or_b32 s98, s98, s99
	s_bfe_u32 s99, s15, 0x40003
	s_or_b32 s98, s98, s99
	s_and_b32 s99, s15, 0xffffff00
	s_or_b32 s98, s98, s99
	s_cmpk_lt_u32 s15, 0x100
	s_cselect_b32 s98, s15, s98
	s_ashr_i32 s19, s98, 4
	s_mul_hi_i32 s22, s19, 0x55555556
	s_lshr_b32 s23, s22, 31
	s_add_i32 s22, s22, s23
	s_mul_i32 s23, s22, 3
	s_sub_i32 s36, s19, s23
	s_mul_hi_i32 s23, s22, 0x2aaaaaab
	s_lshr_b32 s26, s23, 31
	s_add_i32 s23, s23, s26
	s_mul_i32 s23, s23, 6
	s_mul_hi_i32 s19, s19, 0x38e38e39
	s_lshr_b32 s14, s15, 8
	s_sub_i32 s58, s22, s23
	s_lshr_b32 s22, s19, 31
	s_ashr_i32 s19, s19, 2
	s_lshl_b32 s37, s36, 1
	s_add_i32 s14, s14, s98
	s_add_i32 s22, s19, s22
	s_lshr_b32 s19, 16, s37
	v_mov_b32_e32 v135, v32
	s_and_b32 s14, s14, 15
	s_sub_i32 s23, 4, s37
	s_add_i32 s19, s19, -1
	s_lshr_b32 s59, s14, s23
	v_readfirstlane_b32 s17, v135
	s_and_b32 s19, s19, s14
	s_ashr_i32 s23, s22, 31
	s_mul_i32 s14, s36, 0x900
	s_lshl_b32 s60, s58, 7
	s_lshl_b64 s[62:63], s[22:23], 11
	s_add_i32 s22, s60, s14
	s_ashr_i32 s14, s17, 2
	s_lshl_b32 s61, s19, 7
	s_and_b32 s65, s14, -16
	v_and_b32_e32 v136, 15, v135
	s_add_i32 s14, s65, s61
	v_or_b32_e32 v13, s14, v136
	v_lshlrev_b32_e32 v13, s37, v13
	v_add_u32_e32 v14, s59, v13
	v_ashrrev_i32_e32 v15, 31, v14
	v_lshl_add_u64 v[62:63], s[62:63], 0, v[14:15]
	v_lshlrev_b64 v[62:63], 14, v[62:63]
	s_ashr_i32 s23, s22, 31
	v_readlane_b32 s26, v254, 58
	v_lshl_add_u64 v[62:63], s[42:43], 0, v[62:63]
	s_lshl_b64 s[22:23], s[22:23], 1
	v_lshlrev_b64 v[14:15], 7, v[14:15]
	v_readlane_b32 s27, v254, 59
	v_and_b32_e32 v13, 16, v135
	v_lshl_add_u64 v[62:63], v[62:63], 0, s[22:23]
	v_and_b32_e32 v118, 48, v135
	v_mov_b32_e32 v119, v12
	v_lshl_add_u64 v[14:15], s[26:27], 0, v[14:15]
	v_lshlrev_b32_e32 v78, 2, v13
	v_mov_b32_e32 v79, v12
	v_lshl_add_u64 v[70:71], v[62:63], 0, v[118:119]
	v_lshl_add_u64 v[14:15], v[14:15], 0, v[78:79]
	s_add_i32 s14, s61, 0xffffff80
	v_ashrrev_i32_e32 v33, 1, v135
	s_cmp_lt_u32 s15, s10
	s_cbranch_scc0 .Ldil_qskip
	global_load_dwordx4 v[222:225], v[70:71], off
	global_load_dwordx4 v[226:229], v[70:71], off offset:64
	global_load_dwordx4 v[242:245], v[70:71], off offset:128
	global_load_dwordx4 v[246:249], v[70:71], off offset:192
.Ldil_qskip:
	s_nop 0
	global_load_dwordx4 v[78:81], v[14:15], off offset:48
	global_load_dwordx4 v[82:85], v[14:15], off offset:32
	global_load_dwordx4 v[86:89], v[14:15], off offset:16
	global_load_dwordx4 v[90:93], v[14:15], off
	v_add_u32_e32 v14, s14, v33
	v_cmp_lt_i32_e32 vcc, -1, v14
	v_and_b32_e32 v13, 1, v135
	s_sub_i32 s64, 0x7f, s61
	v_cndmask_b32_e32 v14, 0, v14, vcc
	v_lshlrev_b32_e32 v14, s37, v14
	v_add_u32_e32 v94, s59, v14
	v_ashrrev_i32_e32 v95, 31, v94
	v_lshl_add_u64 v[14:15], s[62:63], 0, v[94:95]
	v_lshlrev_b64 v[14:15], 14, v[14:15]
	v_lshl_add_u64 v[14:15], s[42:43], 0, v[14:15]
	v_lshl_add_u64 v[96:97], v[14:15], 0, s[22:23]
	v_lshlrev_b32_e32 v14, 4, v13
	v_mov_b32_e32 v15, v12
	v_lshl_add_u64 v[96:97], v[96:97], 0, v[14:15]
	v_lshlrev_b64 v[94:95], 7, v[94:95]
	global_load_dwordx4 v[98:101], v[96:97], off offset:1536
	global_load_dwordx4 v[102:105], v[96:97], off offset:1568
	v_lshl_add_u64 v[94:95], s[26:27], 0, v[94:95]
	v_lshlrev_b32_e32 v96, 6, v13
	v_mov_b32_e32 v97, v12
	v_lshl_add_u64 v[114:115], v[94:95], 0, v[96:97]
	global_load_dwordx4 v[94:97], v[114:115], off offset:48
	global_load_dwordx4 v[106:109], v[114:115], off offset:32
	global_load_dwordx4 v[110:113], v[114:115], off offset:16
	s_nop 0
	global_load_dwordx4 v[114:117], v[114:115], off
	v_mul_hi_i32 v13, v135, s68
	v_lshrrev_b32_e32 v15, 31, v13
	v_ashrrev_i32_e32 v13, 1, v13
	v_add_u32_e32 v139, v13, v15
	v_cmp_lt_i32_e64 s[38:39], s64, v139
	s_and_saveexec_b64 s[22:23], s[38:39]
	s_cbranch_execz .LBB0_333
	s_mov_b32 s14, 0xffffff4
	v_mul_lo_u32 v13, v139, s14
	s_movk_i32 s14, 0x110
	v_mul_lo_u32 v15, v139, s14
	v_add_lshl_u32 v13, v13, v135, 4
	v_add3_u32 v13, 0, v15, v13
	s_waitcnt vmcnt(10) lgkmcnt(0)
	ds_write_b128 v13, v[4:7] offset:64
.LBB0_333:
	s_or_b64 exec, exec, s[22:23]
	v_add_u32_e32 v13, 0x200, v135
	v_mul_hi_i32 v15, v13, s68
	v_lshrrev_b32_e32 v119, 31, v15
	v_ashrrev_i32_e32 v15, 1, v15
	v_add_u32_e32 v15, v15, v119
	v_cmp_lt_i32_e64 s[38:39], s64, v15
	s_and_saveexec_b64 s[22:23], s[38:39]
	s_cbranch_execz .LBB0_335
	s_mov_b32 s14, 0xffffff4
	v_mul_lo_u32 v119, v15, s14
	s_movk_i32 s14, 0x110
	v_mul_lo_u32 v120, v15, s14
	v_add_lshl_u32 v119, v119, v13, 4
	v_add3_u32 v119, 0, v120, v119
	s_waitcnt vmcnt(10)
	ds_write_b128 v119, v[0:3] offset:64
; #define LAS __attribute__((address_space(3)))
; DI void dil_store(const DilPre& P, bf16x8 (&qf)[4], ldsp lds, const bf16_t* proj, const float* rope, int item, int tid, int wid, int lane) {
;     ...
; #pragma unroll
;     for (int i = 0; i < 6; ++i) {
;         const int e = tid + i * 512, row = e / 12, ch = 4 + (e - row * 12), sp = d.s_k0 + row;
;         if (sp >= 0) *(LAS u32x4*)(Kb + row * DIL_KS + ch * 16) = P.kc[i];
;     }
; #pragma unroll
;     for (int i = 0; i < 8; ++i) {
;         const int e = tid + i * 512, row = e >> 4, ch = e & 15, sp = d.s_k0 + row;
;         if (sp >= 0) *(LAS u32x4*)(Vb + row * DIL_KS + ch * 16) = P.vv[i];
;     }
.LBB0_335:
	s_or_b64 exec, exec, s[22:23]
	v_add_u32_e32 v134, 0x400, v135
	v_mul_hi_i32 v119, v134, s68
	v_lshrrev_b32_e32 v120, 31, v119
	v_ashrrev_i32_e32 v119, 1, v119
	v_add_u32_e32 v138, v119, v120
	v_cmp_lt_i32_e64 s[38:39], s64, v138
	s_and_saveexec_b64 s[22:23], s[38:39]
	s_cbranch_execz .LBB0_337
	s_mov_b32 s14, 0xffffff4
	v_mul_lo_u32 v119, v138, s14
	s_movk_i32 s14, 0x110
	v_mul_lo_u32 v120, v138, s14
	v_add_lshl_u32 v119, v119, v134, 4
	v_add3_u32 v119, 0, v120, v119
	s_waitcnt vmcnt(10)
	ds_write_b128 v119, v[8:11] offset:64
.LBB0_337:
	s_or_b64 exec, exec, s[22:23]
	v_add_u32_e32 v132, 0x600, v135
	v_mul_hi_i32 v119, v132, s68
	v_lshrrev_b32_e32 v120, 31, v119
	v_ashrrev_i32_e32 v119, 1, v119
	v_add_u32_e32 v137, v119, v120
	v_cmp_lt_i32_e64 s[38:39], s64, v137
	s_and_saveexec_b64 s[22:23], s[38:39]
	s_cbranch_execz .LBB0_339
	s_mov_b32 s14, 0xffffff4
	v_mul_lo_u32 v119, v137, s14
	s_movk_i32 s14, 0x110
	v_mul_lo_u32 v120, v137, s14
	v_add_lshl_u32 v119, v119, v132, 4
	v_add3_u32 v119, 0, v120, v119
	s_waitcnt vmcnt(10)
	ds_write_b128 v119, v[16:19] offset:64
.LBB0_339:
	s_or_b64 exec, exec, s[22:23]
	v_add_u32_e32 v129, 0x800, v135
	v_mul_hi_i32 v119, v129, s68
	v_lshrrev_b32_e32 v120, 31, v119
	v_ashrrev_i32_e32 v119, 1, v119
	v_add_u32_e32 v133, v119, v120
	v_cmp_lt_i32_e64 s[38:39], s64, v133
	s_and_saveexec_b64 s[22:23], s[38:39]
	s_cbranch_execz .LBB0_341
	s_mov_b32 s14, 0xffffff4
	v_mul_lo_u32 v119, v133, s14
	s_movk_i32 s14, 0x110
	v_mul_lo_u32 v120, v133, s14
	v_add_lshl_u32 v119, v119, v129, 4
	v_add3_u32 v119, 0, v120, v119
	s_waitcnt vmcnt(10)
	ds_write_b128 v119, v[20:23] offset:64
.LBB0_341:
	s_or_b64 exec, exec, s[22:23]
	v_add_u32_e32 v128, 0xa00, v135
	v_mul_hi_i32 v119, v128, s68
	v_lshrrev_b32_e32 v120, 31, v119
	v_ashrrev_i32_e32 v119, 1, v119
	v_add_u32_e32 v130, v119, v120
	v_cmp_lt_i32_e64 s[38:39], s64, v130
	s_and_saveexec_b64 s[22:23], s[38:39]
	s_cbranch_execz .LBB0_343
	s_mov_b32 s14, 0xffffff4
	v_mul_lo_u32 v119, v130, s14
	s_movk_i32 s14, 0x110
	v_mul_lo_u32 v120, v130, s14
	v_add_lshl_u32 v119, v119, v128, 4
	v_add3_u32 v119, 0, v120, v119
	s_waitcnt vmcnt(10)
	ds_write_b128 v119, v[24:27] offset:64
.LBB0_343:
	s_or_b64 exec, exec, s[22:23]
	v_lshlrev_b32_e32 v119, 4, v135
	v_and_b32_e32 v119, 0xf0, v119
	v_readlane_b32 s14, v254, 46
	v_ashrrev_i32_e32 v131, 4, v135
	v_cmp_lt_i32_e64 s[38:39], s64, v131
	v_add_u32_e32 v120, s14, v119
	s_and_saveexec_b64 s[22:23], s[38:39]
	s_cbranch_execz .LBB0_345
	s_movk_i32 s14, 0x110
	v_mad_u64_u32 v[122:123], s[26:27], v131, s14, v[120:121]
	s_waitcnt vmcnt(10)
	ds_write_b128 v122, v[28:31]
.LBB0_345:
	s_or_b64 exec, exec, s[22:23]
	v_ashrrev_i32_e32 v127, 4, v13
	v_cmp_lt_i32_e64 s[38:39], s64, v127
	s_and_saveexec_b64 s[22:23], s[38:39]
	s_cbranch_execz .LBB0_347
	s_movk_i32 s14, 0x110
	v_mad_u64_u32 v[122:123], s[26:27], v127, s14, v[120:121]
	s_waitcnt vmcnt(10)
	ds_write_b128 v122, v[34:37]
.LBB0_347:
	s_or_b64 exec, exec, s[22:23]
	v_ashrrev_i32_e32 v126, 4, v134
	v_cmp_lt_i32_e64 s[38:39], s64, v126
	s_and_saveexec_b64 s[22:23], s[38:39]
	s_cbranch_execz .LBB0_349
	s_movk_i32 s14, 0x110
	v_mad_u64_u32 v[122:123], s[26:27], v126, s14, v[120:121]
	s_waitcnt vmcnt(10) lgkmcnt(0)
	ds_write_b128 v122, v[38:41]
.LBB0_349:
	s_or_b64 exec, exec, s[22:23]
	v_ashrrev_i32_e32 v125, 4, v132
	v_cmp_lt_i32_e64 s[38:39], s64, v125
	s_and_saveexec_b64 s[22:23], s[38:39]
	s_cbranch_execz .LBB0_351
	s_movk_i32 s14, 0x110
	v_mad_u64_u32 v[122:123], s[26:27], v125, s14, v[120:121]
	s_waitcnt vmcnt(10) lgkmcnt(0)
	ds_write_b128 v122, v[42:45]
.LBB0_351:
	s_or_b64 exec, exec, s[22:23]
	v_ashrrev_i32_e32 v124, 4, v129
	v_cmp_lt_i32_e64 s[38:39], s64, v124
	s_and_saveexec_b64 s[22:23], s[38:39]
	s_cbranch_execz .LBB0_353
	s_movk_i32 s14, 0x110
	v_mad_u64_u32 v[122:123], s[26:27], v124, s14, v[120:121]
	s_waitcnt vmcnt(10)
	ds_write_b128 v122, v[46:49]
.LBB0_353:
	s_or_b64 exec, exec, s[22:23]
	v_ashrrev_i32_e32 v123, 4, v128
	v_cmp_lt_i32_e64 s[38:39], s64, v123
	s_and_saveexec_b64 s[22:23], s[38:39]
	s_cbranch_execz .LBB0_355
	s_movk_i32 s14, 0x110
	v_mad_u64_u32 v[140:141], s[26:27], v123, s14, v[120:121]
	s_waitcnt vmcnt(10)
	ds_write_b128 v140, v[50:53]
.LBB0_355:
	s_or_b64 exec, exec, s[22:23]
	v_add_u32_e32 v119, 0xc00, v135
	v_ashrrev_i32_e32 v122, 4, v119
	v_cmp_lt_i32_e64 s[38:39], s64, v122
	s_and_saveexec_b64 s[22:23], s[38:39]
	s_cbranch_execz .LBB0_357
	s_movk_i32 s14, 0x110
	v_mad_u64_u32 v[140:141], s[26:27], v122, s14, v[120:121]
	s_waitcnt vmcnt(10)
	ds_write_b128 v140, v[54:57]
.LBB0_357:
	s_or_b64 exec, exec, s[22:23]
	v_add_u32_e32 v119, 0xe00, v135
	v_ashrrev_i32_e32 v121, 4, v119
	v_cmp_lt_i32_e64 s[38:39], s64, v121
	s_and_saveexec_b64 s[22:23], s[38:39]
	s_cbranch_execz .LBB0_359
	s_movk_i32 s14, 0x110
	v_mad_u64_u32 v[140:141], s[26:27], v121, s14, v[120:121]
	s_waitcnt vmcnt(10)
	ds_write_b128 v140, v[58:61]

; DI void dil_load(DilPre& P, const bf16_t* proj, int item, int tid, int wid, int lane) {
;     const DilItem d = dil_decode(item);
;     const int kcol = d.qcol + 768, vcol = d.qcol + 1536;
;     const u32x4 z = (u32x4){0u, 0u, 0u, 0u};
; #pragma unroll
;     for (int i = 0; i < 6; ++i) {
;         const int e = tid + i * 512, row = e / 12, ch = 4 + (e - row * 12), sp = d.s_k0 + row;
;         P.kc[i] = z;
;         if (sp >= 0) P.kc[i] = *(const u32x4*)(proj + (d.rowbase + sp * d.r + d.ph) * DIL_N + kcol + ch * 8);
; DI void dil_store(const DilPre& P, bf16x8 (&qf)[4], ldsp lds, const bf16_t* proj, const float* rope, int item, int tid, int wid, int lane) {
;     ...
;         const bf16_t* qsrc = proj + (d.rowbase + tq) * DIL_N + d.qcol + quad * 8;
; #pragma unroll
;         for (int ks = 0; ks < 4; ++ks) qf[ks] = *(const bf16x8*)(qsrc + ks * 32);
;     ...
;         const u32x4 mine = __builtin_bit_cast(u32x4, qf[0]);
;         u32x4 oth, res;
; #pragma unroll
;         for (int jj = 0; jj < 4; ++jj) oth[jj] = (unsigned)__shfl_xor((int)mine[jj], 32);
.LBB0_361:
	s_or_b64 exec, exec, s[26:27]
	v_and_b32_e32 v33, 64, v233
	v_xor_b32_e32 v14, 32, v233
	v_add_u32_e32 v33, 64, v33
	v_cmp_lt_i32_e32 vcc, v14, v33
	s_add_i32 s14, s15, s10
	s_cmpk_gt_i32 s14, 0x8ff
	v_cndmask_b32_e32 v14, v233, v14, vcc
	v_lshlrev_b32_e32 v119, 2, v14
	s_waitcnt vmcnt(0)
	v_mov_b32_e32 v74, v222
	v_mov_b32_e32 v75, v223
	v_mov_b32_e32 v76, v224
	v_mov_b32_e32 v77, v225
	v_mov_b32_e32 v62, v226
	v_mov_b32_e32 v63, v227
	v_mov_b32_e32 v64, v228
	v_mov_b32_e32 v65, v229
	v_mov_b32_e32 v66, v242
	v_mov_b32_e32 v67, v243
	v_mov_b32_e32 v68, v244
	v_mov_b32_e32 v69, v245
	v_mov_b32_e32 v70, v246
	v_mov_b32_e32 v71, v247
	v_mov_b32_e32 v72, v248
	v_mov_b32_e32 v73, v249
	ds_bpermute_b32 v99, v119, v74
	ds_bpermute_b32 v98, v119, v75
	ds_bpermute_b32 v97, v119, v76
	ds_bpermute_b32 v96, v119, v77
	s_cselect_b64 s[56:57], -1, 0
	s_and_b64 vcc, exec, s[56:57]
	s_waitcnt lgkmcnt(0)
	s_barrier
	s_cbranch_vccnz .LBB0_391
	s_and_b32 s99, s14, 7
	s_lshl_b32 s99, s99, 5
	s_bfe_u32 s100, s14, 0x10007
	s_lshl_b32 s100, s100, 4
	s_or_b32 s99, s99, s100
	s_bfe_u32 s100, s14, 0x40003
	s_or_b32 s99, s99, s100
	s_and_b32 s100, s14, 0xffffff00
	s_or_b32 s99, s99, s100
	s_lshr_b32 s22, s14, 8
	s_add_i32 s22, s22, s99
	s_and_b32 s23, s22, 15
	s_ashr_i32 s22, s99, 4
	s_mul_hi_i32 s26, s22, 0x55555556
	s_lshr_b32 s27, s26, 31
	s_add_i32 s26, s26, s27
	s_mul_i32 s27, s26, 3
	s_sub_i32 s30, s22, s27
	s_mul_hi_i32 s27, s26, 0x2aaaaaab
	s_lshr_b32 s31, s27, 31
	s_add_i32 s27, s27, s31
	s_mul_i32 s27, s27, 6
	s_mul_hi_i32 s22, s22, 0x38e38e39
	s_sub_i32 s31, s26, s27
	s_lshr_b32 s26, s22, 31
	s_ashr_i32 s22, s22, 2
	s_lshl_b32 s38, s30, 1
	s_add_i32 s22, s22, s26
	s_lshr_b32 s26, 16, s38
	s_sub_i32 s27, 4, s38
	s_add_i32 s26, s26, -1
	s_lshr_b32 s35, s23, s27
	s_and_b32 s34, s26, s23
	s_ashr_i32 s23, s22, 31
	s_lshl_b64 s[26:27], s[22:23], 11
	s_mulk_i32 s30, 0x900
	s_lshl_b32 s22, s31, 7
	s_add_i32 s22, s22, s30
	s_lshl_b32 s34, s34, 7
	s_ashr_i32 s23, s22, 31
	s_addk_i32 s34, 0xff80
	s_or_b32 s26, s26, s35
	s_lshl_b64 s[22:23], s[22:23], 1
	v_mov_b32_e32 v2, v12
	v_mov_b32_e32 v3, v12
	s_add_u32 s30, s42, s22
	v_add_u32_e32 v8, s34, v139
	v_mov_b32_e32 v0, v12
	v_mov_b32_e32 v1, v12
	v_mov_b64_e32 v[6:7], v[2:3]
	s_addc_u32 s31, s43, s23
	v_cmp_lt_i32_e32 vcc, -1, v8
	v_mov_b64_e32 v[4:5], v[0:1]
	s_and_saveexec_b64 s[22:23], vcc
	s_cbranch_execz .LBB0_364
	s_mov_b32 s35, 0x1ffffff4
	v_lshlrev_b32_e32 v4, s38, v8
	v_mov_b32_e32 v5, v12
	v_mul_lo_u32 v6, v139, s35
	v_lshl_add_u64 v[4:5], s[26:27], 0, v[4:5]
	v_lshlrev_b64 v[4:5], 14, v[4:5]
	v_add_lshl_u32 v6, v6, v135, 3
	v_lshl_add_u64 v[4:5], s[30:31], 0, v[4:5]
	v_ashrrev_i32_e32 v7, 31, v6
	v_lshl_add_u64 v[4:5], v[6:7], 1, v[4:5]
	global_load_dwordx4 v[4:7], v[4:5], off offset:1600
.LBB0_364:
	s_or_b64 exec, exec, s[22:23]
	s_add_i32 s101, s34, 0x80
	s_add_i32 s101, s101, s65
	v_or_b32_e32 v248, s101, v136
	v_lshlrev_b32_e32 v248, s38, v248
	v_mov_b32_e32 v249, v12
	v_lshl_add_u64 v[248:249], s[26:27], 0, v[248:249]
	v_lshlrev_b64 v[248:249], 14, v[248:249]
	v_lshl_add_u64 v[248:249], s[30:31], 0, v[248:249]
	v_and_b32_e32 v246, 48, v135
	v_mov_b32_e32 v247, v12
	v_lshl_add_u64 v[248:249], v[248:249], 0, v[246:247]
	global_load_dwordx4 v[222:225], v[248:249], off
	global_load_dwordx4 v[226:229], v[248:249], off offset:64
	global_load_dwordx4 v[242:245], v[248:249], off offset:128
	global_load_dwordx4 v[246:249], v[248:249], off offset:192
	v_add_u32_e32 v8, s34, v15
	v_cmp_lt_i32_e32 vcc, -1, v8
	s_and_saveexec_b64 s[22:23], vcc
	s_cbranch_execz .LBB0_366
	s_mov_b32 s35, 0x1ffffff4
	v_lshlrev_b32_e32 v0, s38, v8
	v_mov_b32_e32 v1, v12
	v_mul_lo_u32 v2, v15, s35
	v_lshl_add_u64 v[0:1], s[26:27], 0, v[0:1]
	v_lshlrev_b64 v[0:1], 14, v[0:1]
	v_add_lshl_u32 v2, v2, v13, 3
	v_lshl_add_u64 v[0:1], s[30:31], 0, v[0:1]
	v_ashrrev_i32_e32 v3, 31, v2
	v_lshl_add_u64 v[0:1], v[2:3], 1, v[0:1]
	global_load_dwordx4 v[0:3], v[0:1], off offset:1600

; __global__ void __launch_bounds__(NTHREADS, 2) megak(Params p) {
;     ...
;                 dil_attn_phase(lds, PJ, par ? OBUF2 : OBUF, LSE + par * LSE_SLAB, ROPE, SLAB_B * 288, pv, tid, wid, lane);
;                 if (gridDim.x == 256) {
;                     const int grp = blockIdx.x >> 3;
;                     for (int j = 0; j < 2; ++j) mem_attn_item(lds, PJ, DIL_N, DB_QM, DB_GATE, kvl, BR, st.b0, ((blockIdx.x & 7) * 2 + j) + 16 * grp, tid, wid, lane, j == 0);
;                 } else
;                 for (int it = blockIdx.x; it < SLAB_B * 64; it += gridDim.x) mem_attn_item(lds, PJ, DIL_N, DB_QM, DB_GATE, kvl, BR, st.b0, it, tid, wid, lane);
.LBB0_436:
	s_nop 0
	s_nop 0
	s_nop 0
	s_nop 0
	s_nop 0
	s_nop 0
	s_nop 0
	v_readlane_b32 s72, v254, 58
	v_readlane_b32 s73, v254, 59
